# differential-attention finishing pass: four rows' dependent chains interleaved instruction by instruction (no s_nop pads)
# speedup vs baseline: 1.0041x; 1.0022x over previous
; __device__ __forceinline__ void phase_attn(const Params& p, int l, unsigned char* smem) {
;     ...
;             for (int i = 0; i < 32; ++i) {
;                 const int qrow = w * 32 + i;
;                 const float2 a0 = *(const float2*)(blk + (size_t)qrow * 128 + lane * 2);
;                 const float2 a1 = *(const float2*)(blk + (size_t)(256 + qrow) * 128 + lane * 2);
;                 const unsigned zz = *(const unsigned*)(p.sz + (grow0 + qrow) * D + hh * 128 + lane * 2);
;                 const float o0 = a0.x - lam * a1.x, o1 = a0.y - lam * a1.y;
;                 float ss = o0 * o0 + o1 * o1;
;                 ss = wave_sum64(ss);
.Ldv2fin_loop:
	v_lshl_add_u64 v[8:9], v[220:221], 0, s[4:5]
	v_lshl_add_u64 v[10:11], v[222:223], 0, s[4:5]
	v_lshl_add_u64 v[112:113], v[6:7], 0, s[82:83]
	v_lshl_add_u64 v[128:129], v[4:5], 0, s[82:83]
	v_lshl_add_u64 v[18:19], v[8:9], 0, s[10:11]
	v_lshl_add_u64 v[20:21], v[10:11], 0, s[10:11]
	v_lshl_add_u64 v[114:115], v[112:113], 0, s[10:11]
	v_lshl_add_u64 v[116:117], v[114:115], 0, s[10:11]
	v_lshl_add_u64 v[118:119], v[116:117], 0, s[10:11]
	v_lshl_add_u64 v[120:121], v[118:119], 0, s[10:11]
	v_lshl_add_u64 v[122:123], v[120:121], 0, s[10:11]
	v_lshl_add_u64 v[124:125], v[122:123], 0, s[10:11]
	v_lshl_add_u64 v[126:127], v[124:125], 0, s[10:11]
	v_lshl_add_u64 v[130:131], v[128:129], 0, s[10:11]
	v_lshl_add_u64 v[132:133], v[130:131], 0, s[10:11]
	v_lshl_add_u64 v[134:135], v[132:133], 0, s[10:11]
	v_lshl_add_u64 v[136:137], v[134:135], 0, s[10:11]
	v_lshl_add_u64 v[138:139], v[136:137], 0, s[10:11]
	v_lshl_add_u64 v[140:141], v[138:139], 0, s[10:11]
	v_lshl_add_u64 v[142:143], v[140:141], 0, s[10:11]
	global_load_dwordx2 v[30:31], v[8:9], off
	global_load_dwordx2 v[32:33], v[10:11], off
	global_load_dword v94, v[112:113], off
	global_load_dwordx2 v[34:35], v[8:9], off offset:512
	global_load_dwordx2 v[36:37], v[10:11], off offset:512
	global_load_dword v95, v[112:113], off offset:2048
	global_load_dwordx2 v[38:39], v[8:9], off offset:1024
	global_load_dwordx2 v[40:41], v[10:11], off offset:1024
	global_load_dword v96, v[114:115], off
	global_load_dwordx2 v[42:43], v[8:9], off offset:1536
	global_load_dwordx2 v[44:45], v[10:11], off offset:1536
	global_load_dword v97, v[114:115], off offset:2048
	global_load_dwordx2 v[46:47], v[8:9], off offset:2048
	global_load_dwordx2 v[48:49], v[10:11], off offset:2048
	global_load_dword v98, v[116:117], off
	global_load_dwordx2 v[50:51], v[8:9], off offset:2560
	global_load_dwordx2 v[52:53], v[10:11], off offset:2560
	global_load_dword v99, v[116:117], off offset:2048
	global_load_dwordx2 v[54:55], v[8:9], off offset:3072
	global_load_dwordx2 v[56:57], v[10:11], off offset:3072
	global_load_dword v100, v[118:119], off
	global_load_dwordx2 v[58:59], v[8:9], off offset:3584
	global_load_dwordx2 v[60:61], v[10:11], off offset:3584
	global_load_dword v101, v[118:119], off offset:2048
	global_load_dwordx2 v[62:63], v[18:19], off
	global_load_dwordx2 v[64:65], v[20:21], off
	global_load_dword v102, v[120:121], off
	global_load_dwordx2 v[66:67], v[18:19], off offset:512
	global_load_dwordx2 v[68:69], v[20:21], off offset:512
	global_load_dword v103, v[120:121], off offset:2048
	global_load_dwordx2 v[70:71], v[18:19], off offset:1024
	global_load_dwordx2 v[72:73], v[20:21], off offset:1024
	global_load_dword v104, v[122:123], off
	global_load_dwordx2 v[74:75], v[18:19], off offset:1536
	global_load_dwordx2 v[76:77], v[20:21], off offset:1536
	global_load_dword v105, v[122:123], off offset:2048
	global_load_dwordx2 v[78:79], v[18:19], off offset:2048
	global_load_dwordx2 v[80:81], v[20:21], off offset:2048
	global_load_dword v106, v[124:125], off
	global_load_dwordx2 v[82:83], v[18:19], off offset:2560
	global_load_dwordx2 v[84:85], v[20:21], off offset:2560
	global_load_dword v107, v[124:125], off offset:2048
	global_load_dwordx2 v[86:87], v[18:19], off offset:3072
	global_load_dwordx2 v[88:89], v[20:21], off offset:3072
	global_load_dword v108, v[126:127], off
	global_load_dwordx2 v[90:91], v[18:19], off offset:3584
	global_load_dwordx2 v[92:93], v[20:21], off offset:3584
	global_load_dword v109, v[126:127], off offset:2048
	s_add_u32 s4, s4, 0x2000
	s_addc_u32 s5, s5, 0
	v_lshl_add_u64 v[4:5], v[4:5], 0, s[12:13]
	v_lshl_add_u64 v[6:7], v[6:7], 0, s[12:13]
	s_waitcnt vmcnt(36)
	v_fma_f32 v31, -v17, v33, v31
	v_fma_f32 v35, -v17, v37, v35
	v_fma_f32 v39, -v17, v41, v39
	v_fma_f32 v43, -v17, v45, v43
	v_fma_f32 v30, -v17, v32, v30
	v_fma_f32 v34, -v17, v36, v34
	v_fma_f32 v38, -v17, v40, v38
	v_fma_f32 v42, -v17, v44, v42
	v_mul_f32_e32 v33, v31, v31
	v_mul_f32_e32 v37, v35, v35
	v_mul_f32_e32 v41, v39, v39
	v_mul_f32_e32 v45, v43, v43
	v_fmac_f32_e32 v33, v30, v30
	v_fmac_f32_e32 v37, v34, v34
	v_fmac_f32_e32 v41, v38, v38
	v_fmac_f32_e32 v45, v42, v42
	v_lshlrev_b32_e32 v32, 16, v94
	v_lshlrev_b32_e32 v36, 16, v95
	v_lshlrev_b32_e32 v40, 16, v96
	v_lshlrev_b32_e32 v44, 16, v97
	v_and_b32_e32 v94, 0xffff0000, v94
	v_and_b32_e32 v95, 0xffff0000, v95
	v_and_b32_e32 v96, 0xffff0000, v96
	v_and_b32_e32 v97, 0xffff0000, v97
	v_add_f32_dpp v33, v33, v33 quad_perm:[1,0,3,2] row_mask:0xf bank_mask:0xf bound_ctrl:1
	v_add_f32_dpp v37, v37, v37 quad_perm:[1,0,3,2] row_mask:0xf bank_mask:0xf bound_ctrl:1
	v_add_f32_dpp v41, v41, v41 quad_perm:[1,0,3,2] row_mask:0xf bank_mask:0xf bound_ctrl:1
	v_add_f32_dpp v45, v45, v45 quad_perm:[1,0,3,2] row_mask:0xf bank_mask:0xf bound_ctrl:1
	v_add_f32_dpp v33, v33, v33 quad_perm:[2,3,0,1] row_mask:0xf bank_mask:0xf bound_ctrl:1
	v_add_f32_dpp v37, v37, v37 quad_perm:[2,3,0,1] row_mask:0xf bank_mask:0xf bound_ctrl:1
	v_add_f32_dpp v41, v41, v41 quad_perm:[2,3,0,1] row_mask:0xf bank_mask:0xf bound_ctrl:1
	v_add_f32_dpp v45, v45, v45 quad_perm:[2,3,0,1] row_mask:0xf bank_mask:0xf bound_ctrl:1
	v_add_f32_dpp v33, v33, v33 row_half_mirror row_mask:0xf bank_mask:0xf bound_ctrl:1
	v_add_f32_dpp v37, v37, v37 row_half_mirror row_mask:0xf bank_mask:0xf bound_ctrl:1
	v_add_f32_dpp v41, v41, v41 row_half_mirror row_mask:0xf bank_mask:0xf bound_ctrl:1
	v_add_f32_dpp v45, v45, v45 row_half_mirror row_mask:0xf bank_mask:0xf bound_ctrl:1
	v_add_f32_dpp v33, v33, v33 row_mirror row_mask:0xf bank_mask:0xf bound_ctrl:1
	v_add_f32_dpp v37, v37, v37 row_mirror row_mask:0xf bank_mask:0xf bound_ctrl:1
; __device__ __forceinline__ void phase_attn(const Params& p, int l, unsigned char* smem) {
;     ...
;                 ss = wave_sum64(ss);
;                 const float rstd = rsqrtf(ss * (1.0f / 128.0f) + EPS) * post;
;                 const float z0 = __uint_as_float(zz << 16), z1 = __uint_as_float(zz & 0xffff0000u);
;                 *(unsigned*)(p.og + (grow0 + qrow) * D + hh * 128 + lane * 2) = pk_bf16(o0 * rstd * g0 * z0, o1 * rstd * g1 * z1);
	v_add_f32_dpp v41, v41, v41 row_mirror row_mask:0xf bank_mask:0xf bound_ctrl:1
	v_add_f32_dpp v45, v45, v45 row_mirror row_mask:0xf bank_mask:0xf bound_ctrl:1
	v_mov_b32_e32 v144, v33
	v_mov_b32_e32 v145, v37
	v_mov_b32_e32 v146, v41
	v_mov_b32_e32 v147, v45
	v_permlane16_swap_b32_e32 v33, v144
	v_permlane16_swap_b32_e32 v37, v145
	v_permlane16_swap_b32_e32 v41, v146
	v_permlane16_swap_b32_e32 v45, v147
	v_add_f32_e32 v33, v33, v144
	v_add_f32_e32 v37, v37, v145
	v_add_f32_e32 v41, v41, v146
	v_add_f32_e32 v45, v45, v147
	v_mov_b32_e32 v144, v33
	v_mov_b32_e32 v145, v37
	v_mov_b32_e32 v146, v41
	v_mov_b32_e32 v147, v45
	v_permlane32_swap_b32_e32 v33, v144
	v_permlane32_swap_b32_e32 v37, v145
	v_permlane32_swap_b32_e32 v41, v146
	v_permlane32_swap_b32_e32 v45, v147
	v_add_f32_e32 v33, v33, v144
	v_add_f32_e32 v37, v37, v145
	v_add_f32_e32 v41, v41, v146
	v_add_f32_e32 v45, v45, v147
	v_fmamk_f32 v33, v33, 0x3c000000, v236
	v_fmamk_f32 v37, v37, 0x3c000000, v236
	v_fmamk_f32 v41, v41, 0x3c000000, v236
	v_fmamk_f32 v45, v45, 0x3c000000, v236
	v_mul_f32_e32 v144, 0x4b800000, v33
	v_mul_f32_e32 v145, 0x4b800000, v37
	v_mul_f32_e32 v146, 0x4b800000, v41
	v_mul_f32_e32 v147, 0x4b800000, v45
	v_cmp_gt_f32_e64 s[14:15], s7, v33
	v_cmp_gt_f32_e64 s[16:17], s7, v37
	v_cmp_gt_f32_e64 s[18:19], s7, v41
	v_cmp_gt_f32_e64 s[20:21], s7, v45
	v_cndmask_b32_e64 v33, v33, v144, s[14:15]
	v_cndmask_b32_e64 v37, v37, v145, s[16:17]
	v_cndmask_b32_e64 v41, v41, v146, s[18:19]
	v_cndmask_b32_e64 v45, v45, v147, s[20:21]
	v_rsq_f32_e32 v33, v33
	v_rsq_f32_e32 v37, v37
	v_rsq_f32_e32 v41, v41
	v_rsq_f32_e32 v45, v45
	v_mul_f32_e32 v144, 0x45800000, v33
	v_mul_f32_e32 v145, 0x45800000, v37
	v_mul_f32_e32 v146, 0x45800000, v41
	v_mul_f32_e32 v147, 0x45800000, v45
	v_cndmask_b32_e64 v33, v33, v144, s[14:15]
	v_cndmask_b32_e64 v37, v37, v145, s[16:17]
	v_cndmask_b32_e64 v41, v41, v146, s[18:19]
	v_cndmask_b32_e64 v45, v45, v147, s[20:21]
	v_mul_f32_e32 v33, v235, v33
	v_mul_f32_e32 v37, v235, v37
	v_mul_f32_e32 v41, v235, v41
	v_mul_f32_e32 v45, v235, v45
	v_mul_f32_e32 v31, v31, v33
	v_mul_f32_e32 v35, v35, v37
	v_mul_f32_e32 v39, v39, v41
	v_mul_f32_e32 v43, v43, v45
	v_mul_f32_e32 v30, v30, v33
	v_mul_f32_e32 v34, v34, v37
	v_mul_f32_e32 v38, v38, v41
	v_mul_f32_e32 v42, v42, v45
	v_mul_f32_e32 v31, v3, v31
	v_mul_f32_e32 v35, v3, v35
	v_mul_f32_e32 v39, v3, v39
	v_mul_f32_e32 v43, v3, v43
	v_mul_f32_e32 v30, v2, v30
	v_mul_f32_e32 v34, v2, v34
	v_mul_f32_e32 v38, v2, v38
	v_mul_f32_e32 v42, v2, v42
	v_mul_f32_e32 v94, v31, v94
	v_mul_f32_e32 v95, v35, v95
	v_mul_f32_e32 v96, v39, v96
	v_mul_f32_e32 v97, v43, v97
	v_mul_f32_e32 v30, v30, v32
	v_mul_f32_e32 v34, v34, v36
	v_mul_f32_e32 v38, v38, v40
	v_mul_f32_e32 v42, v42, v44
	v_cvt_pk_bf16_f32 v94, v30, v94
	v_cvt_pk_bf16_f32 v95, v34, v95
	v_cvt_pk_bf16_f32 v96, v38, v96
	v_cvt_pk_bf16_f32 v97, v42, v97
	global_store_dword v[128:129], v94, off
	global_store_dword v[128:129], v95, off offset:2048
	global_store_dword v[130:131], v96, off
	global_store_dword v[130:131], v97, off offset:2048
	s_waitcnt vmcnt(28)
	v_fma_f32 v47, -v17, v49, v47
	v_fma_f32 v51, -v17, v53, v51
	v_fma_f32 v55, -v17, v57, v55
	v_fma_f32 v59, -v17, v61, v59
	v_fma_f32 v46, -v17, v48, v46
	v_fma_f32 v50, -v17, v52, v50
	v_fma_f32 v54, -v17, v56, v54
	v_fma_f32 v58, -v17, v60, v58
	v_mul_f32_e32 v49, v47, v47
	v_mul_f32_e32 v53, v51, v51
	v_mul_f32_e32 v57, v55, v55
	v_mul_f32_e32 v61, v59, v59
	v_fmac_f32_e32 v49, v46, v46
	v_fmac_f32_e32 v53, v50, v50
	v_fmac_f32_e32 v57, v54, v54
	v_fmac_f32_e32 v61, v58, v58
	v_lshlrev_b32_e32 v48, 16, v98
	v_lshlrev_b32_e32 v52, 16, v99
	v_lshlrev_b32_e32 v56, 16, v100
	v_lshlrev_b32_e32 v60, 16, v101
	v_and_b32_e32 v98, 0xffff0000, v98
	v_and_b32_e32 v99, 0xffff0000, v99
	v_and_b32_e32 v100, 0xffff0000, v100
	v_and_b32_e32 v101, 0xffff0000, v101
	v_add_f32_dpp v49, v49, v49 quad_perm:[1,0,3,2] row_mask:0xf bank_mask:0xf bound_ctrl:1
	v_add_f32_dpp v53, v53, v53 quad_perm:[1,0,3,2] row_mask:0xf bank_mask:0xf bound_ctrl:1
	v_add_f32_dpp v57, v57, v57 quad_perm:[1,0,3,2] row_mask:0xf bank_mask:0xf bound_ctrl:1
	v_add_f32_dpp v61, v61, v61 quad_perm:[1,0,3,2] row_mask:0xf bank_mask:0xf bound_ctrl:1
	v_add_f32_dpp v49, v49, v49 quad_perm:[2,3,0,1] row_mask:0xf bank_mask:0xf bound_ctrl:1
	v_add_f32_dpp v53, v53, v53 quad_perm:[2,3,0,1] row_mask:0xf bank_mask:0xf bound_ctrl:1
	v_add_f32_dpp v57, v57, v57 quad_perm:[2,3,0,1] row_mask:0xf bank_mask:0xf bound_ctrl:1
	v_add_f32_dpp v61, v61, v61 quad_perm:[2,3,0,1] row_mask:0xf bank_mask:0xf bound_ctrl:1
	v_add_f32_dpp v49, v49, v49 row_half_mirror row_mask:0xf bank_mask:0xf bound_ctrl:1
	v_add_f32_dpp v53, v53, v53 row_half_mirror row_mask:0xf bank_mask:0xf bound_ctrl:1
	v_add_f32_dpp v57, v57, v57 row_half_mirror row_mask:0xf bank_mask:0xf bound_ctrl:1
	v_add_f32_dpp v61, v61, v61 row_half_mirror row_mask:0xf bank_mask:0xf bound_ctrl:1
	v_add_f32_dpp v49, v49, v49 row_mirror row_mask:0xf bank_mask:0xf bound_ctrl:1
	v_add_f32_dpp v53, v53, v53 row_mirror row_mask:0xf bank_mask:0xf bound_ctrl:1
	v_add_f32_dpp v57, v57, v57 row_mirror row_mask:0xf bank_mask:0xf bound_ctrl:1
	v_add_f32_dpp v61, v61, v61 row_mirror row_mask:0xf bank_mask:0xf bound_ctrl:1
	v_mov_b32_e32 v144, v49
	v_mov_b32_e32 v145, v53
	v_mov_b32_e32 v146, v57
	v_mov_b32_e32 v147, v61
	v_permlane16_swap_b32_e32 v49, v144
	v_permlane16_swap_b32_e32 v53, v145
	v_permlane16_swap_b32_e32 v57, v146
	v_permlane16_swap_b32_e32 v61, v147
	v_add_f32_e32 v49, v49, v144
	v_add_f32_e32 v53, v53, v145
	v_add_f32_e32 v57, v57, v146
	v_add_f32_e32 v61, v61, v147
	v_mov_b32_e32 v144, v49
	v_mov_b32_e32 v145, v53
; __device__ __forceinline__ void phase_attn(const Params& p, int l, unsigned char* smem) {
;     ...
;                 ss = wave_sum64(ss);
;                 const float rstd = rsqrtf(ss * (1.0f / 128.0f) + EPS) * post;
;                 const float z0 = __uint_as_float(zz << 16), z1 = __uint_as_float(zz & 0xffff0000u);
;                 *(unsigned*)(p.og + (grow0 + qrow) * D + hh * 128 + lane * 2) = pk_bf16(o0 * rstd * g0 * z0, o1 * rstd * g1 * z1);
	v_mov_b32_e32 v146, v57
	v_mov_b32_e32 v147, v61
	v_permlane32_swap_b32_e32 v49, v144
	v_permlane32_swap_b32_e32 v53, v145
	v_permlane32_swap_b32_e32 v57, v146
	v_permlane32_swap_b32_e32 v61, v147
	v_add_f32_e32 v49, v49, v144
	v_add_f32_e32 v53, v53, v145
	v_add_f32_e32 v57, v57, v146
	v_add_f32_e32 v61, v61, v147
	v_fmamk_f32 v49, v49, 0x3c000000, v236
	v_fmamk_f32 v53, v53, 0x3c000000, v236
	v_fmamk_f32 v57, v57, 0x3c000000, v236
	v_fmamk_f32 v61, v61, 0x3c000000, v236
	v_mul_f32_e32 v144, 0x4b800000, v49
	v_mul_f32_e32 v145, 0x4b800000, v53
	v_mul_f32_e32 v146, 0x4b800000, v57
	v_mul_f32_e32 v147, 0x4b800000, v61
	v_cmp_gt_f32_e64 s[14:15], s7, v49
	v_cmp_gt_f32_e64 s[16:17], s7, v53
	v_cmp_gt_f32_e64 s[18:19], s7, v57
	v_cmp_gt_f32_e64 s[20:21], s7, v61
	v_cndmask_b32_e64 v49, v49, v144, s[14:15]
	v_cndmask_b32_e64 v53, v53, v145, s[16:17]
	v_cndmask_b32_e64 v57, v57, v146, s[18:19]
	v_cndmask_b32_e64 v61, v61, v147, s[20:21]
	v_rsq_f32_e32 v49, v49
	v_rsq_f32_e32 v53, v53
	v_rsq_f32_e32 v57, v57
	v_rsq_f32_e32 v61, v61
	v_mul_f32_e32 v144, 0x45800000, v49
	v_mul_f32_e32 v145, 0x45800000, v53
	v_mul_f32_e32 v146, 0x45800000, v57
	v_mul_f32_e32 v147, 0x45800000, v61
	v_cndmask_b32_e64 v49, v49, v144, s[14:15]
	v_cndmask_b32_e64 v53, v53, v145, s[16:17]
	v_cndmask_b32_e64 v57, v57, v146, s[18:19]
	v_cndmask_b32_e64 v61, v61, v147, s[20:21]
	v_mul_f32_e32 v49, v235, v49
	v_mul_f32_e32 v53, v235, v53
	v_mul_f32_e32 v57, v235, v57
	v_mul_f32_e32 v61, v235, v61
	v_mul_f32_e32 v47, v47, v49
	v_mul_f32_e32 v51, v51, v53
	v_mul_f32_e32 v55, v55, v57
	v_mul_f32_e32 v59, v59, v61
	v_mul_f32_e32 v46, v46, v49
	v_mul_f32_e32 v50, v50, v53
	v_mul_f32_e32 v54, v54, v57
	v_mul_f32_e32 v58, v58, v61
	v_mul_f32_e32 v47, v3, v47
	v_mul_f32_e32 v51, v3, v51
	v_mul_f32_e32 v55, v3, v55
	v_mul_f32_e32 v59, v3, v59
	v_mul_f32_e32 v46, v2, v46
	v_mul_f32_e32 v50, v2, v50
	v_mul_f32_e32 v54, v2, v54
	v_mul_f32_e32 v58, v2, v58
	v_mul_f32_e32 v98, v47, v98
	v_mul_f32_e32 v99, v51, v99
	v_mul_f32_e32 v100, v55, v100
	v_mul_f32_e32 v101, v59, v101
	v_mul_f32_e32 v46, v46, v48
	v_mul_f32_e32 v50, v50, v52
	v_mul_f32_e32 v54, v54, v56
	v_mul_f32_e32 v58, v58, v60
	v_cvt_pk_bf16_f32 v98, v46, v98
	v_cvt_pk_bf16_f32 v99, v50, v99
	v_cvt_pk_bf16_f32 v100, v54, v100
	v_cvt_pk_bf16_f32 v101, v58, v101
	global_store_dword v[132:133], v98, off
	global_store_dword v[132:133], v99, off offset:2048
	global_store_dword v[134:135], v100, off
	global_store_dword v[134:135], v101, off offset:2048
	s_waitcnt vmcnt(20)
	v_fma_f32 v63, -v17, v65, v63
	v_fma_f32 v67, -v17, v69, v67
	v_fma_f32 v71, -v17, v73, v71
	v_fma_f32 v75, -v17, v77, v75
	v_fma_f32 v62, -v17, v64, v62
	v_fma_f32 v66, -v17, v68, v66
	v_fma_f32 v70, -v17, v72, v70
	v_fma_f32 v74, -v17, v76, v74
	v_mul_f32_e32 v65, v63, v63
	v_mul_f32_e32 v69, v67, v67
	v_mul_f32_e32 v73, v71, v71
	v_mul_f32_e32 v77, v75, v75
	v_fmac_f32_e32 v65, v62, v62
	v_fmac_f32_e32 v69, v66, v66
	v_fmac_f32_e32 v73, v70, v70
	v_fmac_f32_e32 v77, v74, v74
	v_lshlrev_b32_e32 v64, 16, v102
	v_lshlrev_b32_e32 v68, 16, v103
	v_lshlrev_b32_e32 v72, 16, v104
	v_lshlrev_b32_e32 v76, 16, v105
	v_and_b32_e32 v102, 0xffff0000, v102
	v_and_b32_e32 v103, 0xffff0000, v103
	v_and_b32_e32 v104, 0xffff0000, v104
	v_and_b32_e32 v105, 0xffff0000, v105
	v_add_f32_dpp v65, v65, v65 quad_perm:[1,0,3,2] row_mask:0xf bank_mask:0xf bound_ctrl:1
	v_add_f32_dpp v69, v69, v69 quad_perm:[1,0,3,2] row_mask:0xf bank_mask:0xf bound_ctrl:1
	v_add_f32_dpp v73, v73, v73 quad_perm:[1,0,3,2] row_mask:0xf bank_mask:0xf bound_ctrl:1
	v_add_f32_dpp v77, v77, v77 quad_perm:[1,0,3,2] row_mask:0xf bank_mask:0xf bound_ctrl:1
	v_add_f32_dpp v65, v65, v65 quad_perm:[2,3,0,1] row_mask:0xf bank_mask:0xf bound_ctrl:1
	v_add_f32_dpp v69, v69, v69 quad_perm:[2,3,0,1] row_mask:0xf bank_mask:0xf bound_ctrl:1
	v_add_f32_dpp v73, v73, v73 quad_perm:[2,3,0,1] row_mask:0xf bank_mask:0xf bound_ctrl:1
	v_add_f32_dpp v77, v77, v77 quad_perm:[2,3,0,1] row_mask:0xf bank_mask:0xf bound_ctrl:1
	v_add_f32_dpp v65, v65, v65 row_half_mirror row_mask:0xf bank_mask:0xf bound_ctrl:1
	v_add_f32_dpp v69, v69, v69 row_half_mirror row_mask:0xf bank_mask:0xf bound_ctrl:1
	v_add_f32_dpp v73, v73, v73 row_half_mirror row_mask:0xf bank_mask:0xf bound_ctrl:1
	v_add_f32_dpp v77, v77, v77 row_half_mirror row_mask:0xf bank_mask:0xf bound_ctrl:1
	v_add_f32_dpp v65, v65, v65 row_mirror row_mask:0xf bank_mask:0xf bound_ctrl:1
	v_add_f32_dpp v69, v69, v69 row_mirror row_mask:0xf bank_mask:0xf bound_ctrl:1
	v_add_f32_dpp v73, v73, v73 row_mirror row_mask:0xf bank_mask:0xf bound_ctrl:1
	v_add_f32_dpp v77, v77, v77 row_mirror row_mask:0xf bank_mask:0xf bound_ctrl:1
	v_mov_b32_e32 v144, v65
	v_mov_b32_e32 v145, v69
	v_mov_b32_e32 v146, v73
	v_mov_b32_e32 v147, v77
	v_permlane16_swap_b32_e32 v65, v144
	v_permlane16_swap_b32_e32 v69, v145
	v_permlane16_swap_b32_e32 v73, v146
	v_permlane16_swap_b32_e32 v77, v147
	v_add_f32_e32 v65, v65, v144
	v_add_f32_e32 v69, v69, v145
	v_add_f32_e32 v73, v73, v146
	v_add_f32_e32 v77, v77, v147
	v_mov_b32_e32 v144, v65
	v_mov_b32_e32 v145, v69
	v_mov_b32_e32 v146, v73
	v_mov_b32_e32 v147, v77
	v_permlane32_swap_b32_e32 v65, v144
	v_permlane32_swap_b32_e32 v69, v145
	v_permlane32_swap_b32_e32 v73, v146
	v_permlane32_swap_b32_e32 v77, v147
	v_add_f32_e32 v65, v65, v144
	v_add_f32_e32 v69, v69, v145
	v_add_f32_e32 v73, v73, v146
	v_add_f32_e32 v77, v77, v147
	v_fmamk_f32 v65, v65, 0x3c000000, v236
	v_fmamk_f32 v69, v69, 0x3c000000, v236
	v_fmamk_f32 v73, v73, 0x3c000000, v236
	v_fmamk_f32 v77, v77, 0x3c000000, v236
	v_mul_f32_e32 v144, 0x4b800000, v65
	v_mul_f32_e32 v145, 0x4b800000, v69
; __device__ __forceinline__ void phase_attn(const Params& p, int l, unsigned char* smem) {
;     ...
;                 ss = wave_sum64(ss);
;                 const float rstd = rsqrtf(ss * (1.0f / 128.0f) + EPS) * post;
;                 const float z0 = __uint_as_float(zz << 16), z1 = __uint_as_float(zz & 0xffff0000u);
;                 *(unsigned*)(p.og + (grow0 + qrow) * D + hh * 128 + lane * 2) = pk_bf16(o0 * rstd * g0 * z0, o1 * rstd * g1 * z1);
	v_mul_f32_e32 v146, 0x4b800000, v73
	v_mul_f32_e32 v147, 0x4b800000, v77
	v_cmp_gt_f32_e64 s[14:15], s7, v65
	v_cmp_gt_f32_e64 s[16:17], s7, v69
	v_cmp_gt_f32_e64 s[18:19], s7, v73
	v_cmp_gt_f32_e64 s[20:21], s7, v77
	v_cndmask_b32_e64 v65, v65, v144, s[14:15]
	v_cndmask_b32_e64 v69, v69, v145, s[16:17]
	v_cndmask_b32_e64 v73, v73, v146, s[18:19]
	v_cndmask_b32_e64 v77, v77, v147, s[20:21]
	v_rsq_f32_e32 v65, v65
	v_rsq_f32_e32 v69, v69
	v_rsq_f32_e32 v73, v73
	v_rsq_f32_e32 v77, v77
	v_mul_f32_e32 v144, 0x45800000, v65
	v_mul_f32_e32 v145, 0x45800000, v69
	v_mul_f32_e32 v146, 0x45800000, v73
	v_mul_f32_e32 v147, 0x45800000, v77
	v_cndmask_b32_e64 v65, v65, v144, s[14:15]
	v_cndmask_b32_e64 v69, v69, v145, s[16:17]
	v_cndmask_b32_e64 v73, v73, v146, s[18:19]
	v_cndmask_b32_e64 v77, v77, v147, s[20:21]
	v_mul_f32_e32 v65, v235, v65
	v_mul_f32_e32 v69, v235, v69
	v_mul_f32_e32 v73, v235, v73
	v_mul_f32_e32 v77, v235, v77
	v_mul_f32_e32 v63, v63, v65
	v_mul_f32_e32 v67, v67, v69
	v_mul_f32_e32 v71, v71, v73
	v_mul_f32_e32 v75, v75, v77
	v_mul_f32_e32 v62, v62, v65
	v_mul_f32_e32 v66, v66, v69
	v_mul_f32_e32 v70, v70, v73
	v_mul_f32_e32 v74, v74, v77
	v_mul_f32_e32 v63, v3, v63
	v_mul_f32_e32 v67, v3, v67
	v_mul_f32_e32 v71, v3, v71
	v_mul_f32_e32 v75, v3, v75
	v_mul_f32_e32 v62, v2, v62
	v_mul_f32_e32 v66, v2, v66
	v_mul_f32_e32 v70, v2, v70
	v_mul_f32_e32 v74, v2, v74
	v_mul_f32_e32 v102, v63, v102
	v_mul_f32_e32 v103, v67, v103
	v_mul_f32_e32 v104, v71, v104
	v_mul_f32_e32 v105, v75, v105
	v_mul_f32_e32 v62, v62, v64
	v_mul_f32_e32 v66, v66, v68
	v_mul_f32_e32 v70, v70, v72
	v_mul_f32_e32 v74, v74, v76
	v_cvt_pk_bf16_f32 v102, v62, v102
	v_cvt_pk_bf16_f32 v103, v66, v103
	v_cvt_pk_bf16_f32 v104, v70, v104
	v_cvt_pk_bf16_f32 v105, v74, v105
	global_store_dword v[136:137], v102, off
	global_store_dword v[136:137], v103, off offset:2048
	global_store_dword v[138:139], v104, off
	global_store_dword v[138:139], v105, off offset:2048
	s_waitcnt vmcnt(12)
; __device__ __forceinline__ void phase_attn(const Params& p, int l, unsigned char* smem) {
;     ...
;                 const float2 a0 = *(const float2*)(blk + (size_t)qrow * 128 + lane * 2);
;                 const float2 a1 = *(const float2*)(blk + (size_t)(256 + qrow) * 128 + lane * 2);
;                 const unsigned zz = *(const unsigned*)(p.sz + (grow0 + qrow) * D + hh * 128 + lane * 2);
;                 const float o0 = a0.x - lam * a1.x, o1 = a0.y - lam * a1.y;
;                 float ss = o0 * o0 + o1 * o1;
;                 ss = wave_sum64(ss);
;                 const float rstd = rsqrtf(ss * (1.0f / 128.0f) + EPS) * post;
;                 const float z0 = __uint_as_float(zz << 16), z1 = __uint_as_float(zz & 0xffff0000u);
;                 *(unsigned*)(p.og + (grow0 + qrow) * D + hh * 128 + lane * 2) = pk_bf16(o0 * rstd * g0 * z0, o1 * rstd * g1 * z1);
;             }
;             __syncthreads();
;         }
	v_fma_f32 v79, -v17, v81, v79
	v_fma_f32 v83, -v17, v85, v83
	v_fma_f32 v87, -v17, v89, v87
	v_fma_f32 v91, -v17, v93, v91
	v_fma_f32 v78, -v17, v80, v78
	v_fma_f32 v82, -v17, v84, v82
	v_fma_f32 v86, -v17, v88, v86
	v_fma_f32 v90, -v17, v92, v90
	v_mul_f32_e32 v81, v79, v79
	v_mul_f32_e32 v85, v83, v83
	v_mul_f32_e32 v89, v87, v87
	v_mul_f32_e32 v93, v91, v91
	v_fmac_f32_e32 v81, v78, v78
	v_fmac_f32_e32 v85, v82, v82
	v_fmac_f32_e32 v89, v86, v86
	v_fmac_f32_e32 v93, v90, v90
	v_lshlrev_b32_e32 v80, 16, v106
	v_lshlrev_b32_e32 v84, 16, v107
	v_lshlrev_b32_e32 v88, 16, v108
	v_lshlrev_b32_e32 v92, 16, v109
	v_and_b32_e32 v106, 0xffff0000, v106
	v_and_b32_e32 v107, 0xffff0000, v107
	v_and_b32_e32 v108, 0xffff0000, v108
	v_and_b32_e32 v109, 0xffff0000, v109
	v_add_f32_dpp v81, v81, v81 quad_perm:[1,0,3,2] row_mask:0xf bank_mask:0xf bound_ctrl:1
	v_add_f32_dpp v85, v85, v85 quad_perm:[1,0,3,2] row_mask:0xf bank_mask:0xf bound_ctrl:1
	v_add_f32_dpp v89, v89, v89 quad_perm:[1,0,3,2] row_mask:0xf bank_mask:0xf bound_ctrl:1
	v_add_f32_dpp v93, v93, v93 quad_perm:[1,0,3,2] row_mask:0xf bank_mask:0xf bound_ctrl:1
	v_add_f32_dpp v81, v81, v81 quad_perm:[2,3,0,1] row_mask:0xf bank_mask:0xf bound_ctrl:1
	v_add_f32_dpp v85, v85, v85 quad_perm:[2,3,0,1] row_mask:0xf bank_mask:0xf bound_ctrl:1
	v_add_f32_dpp v89, v89, v89 quad_perm:[2,3,0,1] row_mask:0xf bank_mask:0xf bound_ctrl:1
	v_add_f32_dpp v93, v93, v93 quad_perm:[2,3,0,1] row_mask:0xf bank_mask:0xf bound_ctrl:1
	v_add_f32_dpp v81, v81, v81 row_half_mirror row_mask:0xf bank_mask:0xf bound_ctrl:1
	v_add_f32_dpp v85, v85, v85 row_half_mirror row_mask:0xf bank_mask:0xf bound_ctrl:1
	v_add_f32_dpp v89, v89, v89 row_half_mirror row_mask:0xf bank_mask:0xf bound_ctrl:1
	v_add_f32_dpp v93, v93, v93 row_half_mirror row_mask:0xf bank_mask:0xf bound_ctrl:1
	v_add_f32_dpp v81, v81, v81 row_mirror row_mask:0xf bank_mask:0xf bound_ctrl:1
	v_add_f32_dpp v85, v85, v85 row_mirror row_mask:0xf bank_mask:0xf bound_ctrl:1
	v_add_f32_dpp v89, v89, v89 row_mirror row_mask:0xf bank_mask:0xf bound_ctrl:1
	v_add_f32_dpp v93, v93, v93 row_mirror row_mask:0xf bank_mask:0xf bound_ctrl:1
	v_mov_b32_e32 v144, v81
	v_mov_b32_e32 v145, v85
	v_mov_b32_e32 v146, v89
	v_mov_b32_e32 v147, v93
	v_permlane16_swap_b32_e32 v81, v144
	v_permlane16_swap_b32_e32 v85, v145
	v_permlane16_swap_b32_e32 v89, v146
	v_permlane16_swap_b32_e32 v93, v147
	v_add_f32_e32 v81, v81, v144
	v_add_f32_e32 v85, v85, v145
	v_add_f32_e32 v89, v89, v146
	v_add_f32_e32 v93, v93, v147
	v_mov_b32_e32 v144, v81
	v_mov_b32_e32 v145, v85
	v_mov_b32_e32 v146, v89
	v_mov_b32_e32 v147, v93
	v_permlane32_swap_b32_e32 v81, v144
	v_permlane32_swap_b32_e32 v85, v145
	v_permlane32_swap_b32_e32 v89, v146
	v_permlane32_swap_b32_e32 v93, v147
	v_add_f32_e32 v81, v81, v144
	v_add_f32_e32 v85, v85, v145
	v_add_f32_e32 v89, v89, v146
	v_add_f32_e32 v93, v93, v147
	v_fmamk_f32 v81, v81, 0x3c000000, v236
	v_fmamk_f32 v85, v85, 0x3c000000, v236
	v_fmamk_f32 v89, v89, 0x3c000000, v236
	v_fmamk_f32 v93, v93, 0x3c000000, v236
	v_mul_f32_e32 v144, 0x4b800000, v81
	v_mul_f32_e32 v145, 0x4b800000, v85
	v_mul_f32_e32 v146, 0x4b800000, v89
	v_mul_f32_e32 v147, 0x4b800000, v93
	v_cmp_gt_f32_e64 s[14:15], s7, v81
	v_cmp_gt_f32_e64 s[16:17], s7, v85
	v_cmp_gt_f32_e64 s[18:19], s7, v89
	v_cmp_gt_f32_e64 s[20:21], s7, v93
	v_cndmask_b32_e64 v81, v81, v144, s[14:15]
	v_cndmask_b32_e64 v85, v85, v145, s[16:17]
	v_cndmask_b32_e64 v89, v89, v146, s[18:19]
	v_cndmask_b32_e64 v93, v93, v147, s[20:21]
	v_rsq_f32_e32 v81, v81
	v_rsq_f32_e32 v85, v85
	v_rsq_f32_e32 v89, v89
	v_rsq_f32_e32 v93, v93
	v_mul_f32_e32 v144, 0x45800000, v81
	v_mul_f32_e32 v145, 0x45800000, v85
	v_mul_f32_e32 v146, 0x45800000, v89
	v_mul_f32_e32 v147, 0x45800000, v93
	v_cndmask_b32_e64 v81, v81, v144, s[14:15]
	v_cndmask_b32_e64 v85, v85, v145, s[16:17]
	v_cndmask_b32_e64 v89, v89, v146, s[18:19]
	v_cndmask_b32_e64 v93, v93, v147, s[20:21]
	v_mul_f32_e32 v81, v235, v81
	v_mul_f32_e32 v85, v235, v85
	v_mul_f32_e32 v89, v235, v89
	v_mul_f32_e32 v93, v235, v93
	v_mul_f32_e32 v79, v79, v81
	v_mul_f32_e32 v83, v83, v85
	v_mul_f32_e32 v87, v87, v89
	v_mul_f32_e32 v91, v91, v93
	v_mul_f32_e32 v78, v78, v81
	v_mul_f32_e32 v82, v82, v85
	v_mul_f32_e32 v86, v86, v89
	v_mul_f32_e32 v90, v90, v93
	v_mul_f32_e32 v79, v3, v79
	v_mul_f32_e32 v83, v3, v83
	v_mul_f32_e32 v87, v3, v87
	v_mul_f32_e32 v91, v3, v91
	v_mul_f32_e32 v78, v2, v78
	v_mul_f32_e32 v82, v2, v82
	v_mul_f32_e32 v86, v2, v86
	v_mul_f32_e32 v90, v2, v90
	v_mul_f32_e32 v106, v79, v106
	v_mul_f32_e32 v107, v83, v107
	v_mul_f32_e32 v108, v87, v108
	v_mul_f32_e32 v109, v91, v109
	v_mul_f32_e32 v78, v78, v80
	v_mul_f32_e32 v82, v82, v84
	v_mul_f32_e32 v86, v86, v88
	v_mul_f32_e32 v90, v90, v92
	v_cvt_pk_bf16_f32 v106, v78, v106
	v_cvt_pk_bf16_f32 v107, v82, v107
	v_cvt_pk_bf16_f32 v108, v86, v108
	v_cvt_pk_bf16_f32 v109, v90, v109
	global_store_dword v[140:141], v106, off
	global_store_dword v[140:141], v107, off offset:2048
	global_store_dword v[142:143], v108, off
	global_store_dword v[142:143], v109, off offset:2048
	s_cmpk_eq_i32 s4, 0x4000
	s_cbranch_scc0 .Ldv2fin_loop
	v_readlane_b32 s4, v254, 4
	s_add_i32 s35, s35, s4
	s_movk_i32 s89, 0x3000
	s_movk_i32 s60, 0x1000
	s_cmp_ge_u32 s35, s34
	s_barrier
	s_cbranch_scc0 .LBB0_256
